# XCC-locality check after SEAM(0): 32 serialized sc1 loads batched into one wait
# speedup vs baseline: 1.0021x; 1.0021x over previous
; __device__ __forceinline__ int lane_id() { int l; asm volatile("v_mbcnt_lo_u32_b32 %0, -1, 0\n\tv_mbcnt_hi_u32_b32 %0, -1, %0" : "=v"(l)); return l; }
; __global__ void __launch_bounds__(NTHR, 2) fwd_megakernel(Prm P) {
;     ...
;     if (wave == 0 && lane_id() == 0) {
;         unsigned* ctlw = (unsigned*)(ws + WS_CTL); bool ok = (G == 256) && (bst[0] == 32u);
;         for (int k = 0; k < 32 && ok; ++k) ok = (__hip_atomic_load(ctlw + XL_TAB + (bx & 7) + 8 * k, __ATOMIC_RELAXED, __HIP_MEMORY_SCOPE_AGENT) == xbar.x + 1u);
;         if (!ok) __hip_atomic_store(ctlw + XL_BAD, 1u, __ATOMIC_RELAXED, __HIP_MEMORY_SCOPE_AGENT);
;     }
.LBB0_236:
	global_load_dword v1, v0, s[10:11] sc1
	global_load_dword v2, v0, s[10:11] offset:32 sc1
	global_load_dword v3, v0, s[10:11] offset:64 sc1
	global_load_dword v4, v0, s[10:11] offset:96 sc1
	global_load_dword v5, v0, s[10:11] offset:128 sc1
	global_load_dword v6, v0, s[10:11] offset:160 sc1
	global_load_dword v7, v0, s[10:11] offset:192 sc1
	global_load_dword v8, v0, s[10:11] offset:224 sc1
	global_load_dword v9, v0, s[10:11] offset:256 sc1
	global_load_dword v10, v0, s[10:11] offset:288 sc1
	global_load_dword v11, v0, s[10:11] offset:320 sc1
	global_load_dword v12, v0, s[10:11] offset:352 sc1
	global_load_dword v13, v0, s[10:11] offset:384 sc1
	global_load_dword v14, v0, s[10:11] offset:416 sc1
	global_load_dword v15, v0, s[10:11] offset:448 sc1
	global_load_dword v16, v0, s[10:11] offset:480 sc1
	global_load_dword v17, v0, s[10:11] offset:512 sc1
	global_load_dword v18, v0, s[10:11] offset:544 sc1
	global_load_dword v19, v0, s[10:11] offset:576 sc1
	global_load_dword v20, v0, s[10:11] offset:608 sc1
	global_load_dword v21, v0, s[10:11] offset:640 sc1
	global_load_dword v22, v0, s[10:11] offset:672 sc1
	global_load_dword v23, v0, s[10:11] offset:704 sc1
	global_load_dword v24, v0, s[10:11] offset:736 sc1
	global_load_dword v25, v0, s[10:11] offset:768 sc1
	global_load_dword v26, v0, s[10:11] offset:800 sc1
	global_load_dword v27, v0, s[10:11] offset:832 sc1
	global_load_dword v28, v0, s[10:11] offset:864 sc1
	global_load_dword v29, v0, s[10:11] offset:896 sc1
	global_load_dword v30, v0, s[10:11] offset:928 sc1
	global_load_dword v31, v0, s[10:11] offset:960 sc1
	global_load_dword v32, v0, s[10:11] offset:992 sc1
	s_waitcnt vmcnt(0)
	v_xor_b32_e32 v33, s12, v1
	v_xor_b32_e32 v34, s12, v2
	v_or_b32_e32 v33, v33, v34
	v_xor_b32_e32 v34, s12, v3
	v_or_b32_e32 v33, v33, v34
	v_xor_b32_e32 v34, s12, v4
	v_or_b32_e32 v33, v33, v34
	v_xor_b32_e32 v34, s12, v5
	v_or_b32_e32 v33, v33, v34
	v_xor_b32_e32 v34, s12, v6
	v_or_b32_e32 v33, v33, v34
	v_xor_b32_e32 v34, s12, v7
	v_or_b32_e32 v33, v33, v34
	v_xor_b32_e32 v34, s12, v8
	v_or_b32_e32 v33, v33, v34
	v_xor_b32_e32 v34, s12, v9
	v_or_b32_e32 v33, v33, v34
	v_xor_b32_e32 v34, s12, v10
	v_or_b32_e32 v33, v33, v34
	v_xor_b32_e32 v34, s12, v11
	v_or_b32_e32 v33, v33, v34
	v_xor_b32_e32 v34, s12, v12
	v_or_b32_e32 v33, v33, v34
	v_xor_b32_e32 v34, s12, v13
	v_or_b32_e32 v33, v33, v34
	v_xor_b32_e32 v34, s12, v14
	v_or_b32_e32 v33, v33, v34
	v_xor_b32_e32 v34, s12, v15
	v_or_b32_e32 v33, v33, v34
	v_xor_b32_e32 v34, s12, v16
	v_or_b32_e32 v33, v33, v34
	v_xor_b32_e32 v34, s12, v17
	v_or_b32_e32 v33, v33, v34
	v_xor_b32_e32 v34, s12, v18
	v_or_b32_e32 v33, v33, v34
	v_xor_b32_e32 v34, s12, v19
	v_or_b32_e32 v33, v33, v34
	v_xor_b32_e32 v34, s12, v20
	v_or_b32_e32 v33, v33, v34
	v_xor_b32_e32 v34, s12, v21
	v_or_b32_e32 v33, v33, v34
	v_xor_b32_e32 v34, s12, v22
	v_or_b32_e32 v33, v33, v34
	v_xor_b32_e32 v34, s12, v23
	v_or_b32_e32 v33, v33, v34
	v_xor_b32_e32 v34, s12, v24
	v_or_b32_e32 v33, v33, v34
	v_xor_b32_e32 v34, s12, v25
	v_or_b32_e32 v33, v33, v34
	v_xor_b32_e32 v34, s12, v26
	v_or_b32_e32 v33, v33, v34
	v_xor_b32_e32 v34, s12, v27
	v_or_b32_e32 v33, v33, v34
	v_xor_b32_e32 v34, s12, v28
	v_or_b32_e32 v33, v33, v34
	v_xor_b32_e32 v34, s12, v29
	v_or_b32_e32 v33, v33, v34
	v_xor_b32_e32 v34, s12, v30
	v_or_b32_e32 v33, v33, v34
	v_xor_b32_e32 v34, s12, v31
	v_or_b32_e32 v33, v33, v34
	v_xor_b32_e32 v34, s12, v32
	v_or_b32_e32 v33, v33, v34
	v_cmp_ne_u32_e32 vcc, 0, v33
	s_nop 3
	s_mov_b64 s[8:9], vcc
